# residual epilogues of the w_o (layer 0) and final FFN-down GEMMs: all residual loads issued ahead, counted vmcnt instead of load-wait-store ladder
# speedup vs baseline: 1.0066x; 1.0066x over previous
.LBB0_1454:
	v_lshl_add_u32 v142, s40, 8, v144
	v_lshl_add_u32 v140, s42, 8, v146
	v_ashrrev_i32_e32 v143, 31, v142
	v_ashrrev_i32_e32 v141, 31, v140
	v_lshlrev_b64 v[152:153], 10, v[142:143]
	v_lshl_add_u64 v[156:157], v[152:153], 0, v[140:141]
	v_lshl_add_u64 v[158:159], v[156:157], 2, s[12:13]
	global_load_dwordx4 v[162:165], v[158:159], off
	global_load_dwordx4 v[166:169], v[158:159], off offset:64
	global_load_dwordx4 v[170:173], v[158:159], off offset:512
	global_load_dwordx4 v[174:177], v[158:159], off offset:576
	v_add_u32_e32 v250, 0x10, v142
	v_ashrrev_i32_e32 v251, 31, v250
	v_lshlrev_b64 v[250:251], 10, v[250:251]
	v_lshl_add_u64 v[250:251], v[250:251], 0, v[140:141]
	v_lshl_add_u64 v[250:251], v[250:251], 2, s[12:13]
	global_load_dwordx4 v[178:181], v[250:251], off
	global_load_dwordx4 v[182:185], v[250:251], off offset:64
	global_load_dwordx4 v[186:189], v[250:251], off offset:512
	global_load_dwordx4 v[190:193], v[250:251], off offset:576
	v_add_u32_e32 v252, 0x20, v142
	v_ashrrev_i32_e32 v253, 31, v252
	v_lshlrev_b64 v[252:253], 10, v[252:253]
	v_lshl_add_u64 v[252:253], v[252:253], 0, v[140:141]
	v_lshl_add_u64 v[252:253], v[252:253], 2, s[12:13]
	global_load_dwordx4 v[194:197], v[252:253], off
	global_load_dwordx4 v[198:201], v[252:253], off offset:64
	global_load_dwordx4 v[202:205], v[252:253], off offset:512
	global_load_dwordx4 v[206:209], v[252:253], off offset:576
	v_add_u32_e32 v250, 0x30, v142
	v_ashrrev_i32_e32 v251, 31, v250
	v_lshlrev_b64 v[250:251], 10, v[250:251]
	v_lshl_add_u64 v[250:251], v[250:251], 0, v[140:141]
	v_lshl_add_u64 v[250:251], v[250:251], 2, s[12:13]
	global_load_dwordx4 v[210:213], v[250:251], off
	global_load_dwordx4 v[222:225], v[250:251], off offset:64
	global_load_dwordx4 v[226:229], v[250:251], off offset:512
	global_load_dwordx4 v[230:233], v[250:251], off offset:576
	v_add_u32_e32 v252, 0x80, v142
	v_ashrrev_i32_e32 v253, 31, v252
	v_lshlrev_b64 v[252:253], 10, v[252:253]
	v_lshl_add_u64 v[252:253], v[252:253], 0, v[140:141]
	v_lshl_add_u64 v[252:253], v[252:253], 2, s[12:13]
	global_load_dwordx4 v[234:237], v[252:253], off
	global_load_dwordx4 v[238:241], v[252:253], off offset:64
	global_load_dwordx4 v[242:245], v[252:253], off offset:512
	global_load_dwordx4 v[246:249], v[252:253], off offset:576
	v_lshl_add_u64 v[156:157], v[156:157], 1, s[28:29]
	s_waitcnt vmcnt(19)
	v_pk_add_f32 v[154:155], v[126:127], v[164:165]
	v_pk_add_f32 v[152:153], v[124:125], v[162:163]
	v_cvt_pk_bf16_f32 v125, v154, v155
	v_cvt_pk_bf16_f32 v124, v152, v153
	global_store_dwordx2 v[156:157], v[124:125], off
	v_mul_f32_e32 v151, v153, v153
	v_mul_f32_e32 v153, v155, v155
	v_fmac_f32_e32 v151, v152, v152
	v_fmac_f32_e32 v153, v154, v154
	v_add_f32_e32 v151, v151, v153
	s_waitcnt vmcnt(19)
	v_pk_add_f32 v[126:127], v[122:123], v[168:169]
	v_pk_add_f32 v[124:125], v[120:121], v[166:167]
	v_cvt_pk_bf16_f32 v121, v126, v127
	v_cvt_pk_bf16_f32 v120, v124, v125
	global_store_dwordx2 v[156:157], v[120:121], off offset:32
	v_mul_f32_e32 v125, v125, v125
	v_mul_f32_e32 v127, v127, v127
	v_fmac_f32_e32 v125, v124, v124
	v_fmac_f32_e32 v127, v126, v126
	v_add_f32_e32 v124, v125, v127
	v_add_f32_e32 v124, v151, v124
	s_waitcnt vmcnt(19)
	v_pk_add_f32 v[122:123], v[118:119], v[172:173]
	v_pk_add_f32 v[160:161], v[116:117], v[170:171]
	v_cvt_pk_bf16_f32 v117, v122, v123
	v_cvt_pk_bf16_f32 v116, v160, v161
	global_store_dwordx2 v[156:157], v[116:117], off offset:256
	v_and_b32_e32 v117, 64, v150
	v_mul_f32_e32 v125, v161, v161
	v_mul_f32_e32 v123, v123, v123
	v_xor_b32_e32 v116, 16, v150
	v_add_u32_e32 v117, 64, v117
	v_fmac_f32_e32 v125, v160, v160
	v_fmac_f32_e32 v123, v122, v122
	v_cmp_lt_i32_e32 vcc, v116, v117
	v_add_f32_e32 v122, v125, v123
	v_add_f32_e32 v122, v124, v122
	v_cndmask_b32_e32 v116, v150, v116, vcc
	v_lshlrev_b32_e32 v116, 2, v116
	s_waitcnt vmcnt(19)
	v_pk_add_f32 v[120:121], v[114:115], v[176:177]
	v_pk_add_f32 v[118:119], v[112:113], v[174:175]
	v_mul_f32_e32 v113, v121, v121
	v_mul_f32_e32 v112, v119, v119
	v_fmac_f32_e32 v112, v118, v118
	v_fmac_f32_e32 v113, v120, v120
	v_add_f32_e32 v112, v112, v113
	v_add_f32_e32 v112, v122, v112
	ds_bpermute_b32 v113, v116, v112
	v_xor_b32_e32 v114, 32, v150
	v_cmp_lt_i32_e32 vcc, v114, v117
	v_cvt_pk_bf16_f32 v118, v118, v119
	v_cvt_pk_bf16_f32 v119, v120, v121
	v_cndmask_b32_e32 v114, v150, v114, vcc
	s_waitcnt lgkmcnt(0)
	v_add_f32_e32 v112, v112, v113
	v_lshlrev_b32_e32 v114, 2, v114
	ds_bpermute_b32 v113, v114, v112
	global_store_dwordx2 v[156:157], v[118:119], off offset:288
	s_and_saveexec_b64 s[40:41], s[2:3]
	s_cbranch_execz .LBB0_1456
	v_lshl_add_u64 v[118:119], v[142:143], 2, s[6:7]
	s_waitcnt lgkmcnt(0)
	v_add_f32_e32 v112, v112, v113
	global_atomic_add_f32 v[118:119], v112, off
.LBB0_1456:
	s_or_b64 exec, exec, s[40:41]
	v_or_b32_e32 v112, 16, v142
	s_waitcnt lgkmcnt(0)
	v_ashrrev_i32_e32 v113, 31, v112
	v_lshlrev_b64 v[118:119], 10, v[112:113]
	v_lshl_add_u64 v[122:123], v[118:119], 0, v[140:141]
	v_lshl_add_u64 v[124:125], v[122:123], 2, s[12:13]
	v_lshl_add_u64 v[122:123], v[122:123], 1, s[28:29]
	s_waitcnt vmcnt(19)
	v_pk_add_f32 v[120:121], v[110:111], v[180:181]
	v_pk_add_f32 v[118:119], v[108:109], v[178:179]
	v_cvt_pk_bf16_f32 v109, v120, v121
	v_cvt_pk_bf16_f32 v108, v118, v119
	global_store_dwordx2 v[122:123], v[108:109], off
	v_mul_f32_e32 v115, v119, v119
	v_mul_f32_e32 v117, v121, v121
	v_fmac_f32_e32 v115, v118, v118
	v_fmac_f32_e32 v117, v120, v120
	v_add_f32_e32 v115, v115, v117
	s_waitcnt vmcnt(19)
	v_pk_add_f32 v[110:111], v[106:107], v[184:185]
	v_pk_add_f32 v[108:109], v[104:105], v[182:183]
	v_cvt_pk_bf16_f32 v105, v110, v111
	v_cvt_pk_bf16_f32 v104, v108, v109
	global_store_dwordx2 v[122:123], v[104:105], off offset:32
	v_mul_f32_e32 v109, v109, v109
	v_mul_f32_e32 v111, v111, v111
	v_fmac_f32_e32 v109, v108, v108
	v_fmac_f32_e32 v111, v110, v110
	v_add_f32_e32 v108, v109, v111
	v_add_f32_e32 v108, v115, v108
	s_waitcnt vmcnt(19)
	v_pk_add_f32 v[106:107], v[102:103], v[188:189]
	v_pk_add_f32 v[104:105], v[100:101], v[186:187]
	v_cvt_pk_bf16_f32 v101, v106, v107
	v_cvt_pk_bf16_f32 v100, v104, v105
	global_store_dwordx2 v[122:123], v[100:101], off offset:256
	v_mul_f32_e32 v105, v105, v105
	v_mul_f32_e32 v107, v107, v107
	v_fmac_f32_e32 v105, v104, v104
	v_fmac_f32_e32 v107, v106, v106
	v_add_f32_e32 v104, v105, v107
	v_add_f32_e32 v104, v108, v104
	s_waitcnt vmcnt(19)
	v_pk_add_f32 v[98:99], v[98:99], v[192:193]
	v_pk_add_f32 v[100:101], v[96:97], v[190:191]
	v_mul_f32_e32 v97, v99, v99
	v_mul_f32_e32 v96, v101, v101
	v_fmac_f32_e32 v96, v100, v100
	v_fmac_f32_e32 v97, v98, v98
	v_add_f32_e32 v96, v96, v97
	v_add_f32_e32 v96, v104, v96
	ds_bpermute_b32 v97, v116, v96
	v_cvt_pk_bf16_f32 v100, v100, v101
	v_cvt_pk_bf16_f32 v101, v98, v99
	global_store_dwordx2 v[122:123], v[100:101], off offset:288
	s_waitcnt lgkmcnt(0)
	v_add_f32_e32 v96, v96, v97
	ds_bpermute_b32 v97, v114, v96
	s_and_saveexec_b64 s[40:41], s[2:3]
	s_cbranch_execz .LBB0_1458
	v_lshl_add_u64 v[98:99], v[112:113], 2, s[6:7]
	s_waitcnt lgkmcnt(0)
	v_add_f32_e32 v96, v96, v97
	global_atomic_add_f32 v[98:99], v96, off
.LBB0_1458:
	s_or_b64 exec, exec, s[40:41]
	v_or_b32_e32 v96, 32, v142
	s_waitcnt lgkmcnt(0)
	v_ashrrev_i32_e32 v97, 31, v96
	v_lshlrev_b64 v[98:99], 10, v[96:97]
	v_lshl_add_u64 v[102:103], v[98:99], 0, v[140:141]
	v_lshl_add_u64 v[104:105], v[102:103], 2, s[12:13]
	v_lshl_add_u64 v[102:103], v[102:103], 1, s[28:29]
	s_waitcnt vmcnt(19)
	v_pk_add_f32 v[100:101], v[94:95], v[196:197]
	v_pk_add_f32 v[98:99], v[92:93], v[194:195]
	v_cvt_pk_bf16_f32 v93, v100, v101
	v_cvt_pk_bf16_f32 v92, v98, v99
	global_store_dwordx2 v[102:103], v[92:93], off
	v_mul_f32_e32 v99, v99, v99
	v_mul_f32_e32 v101, v101, v101
	v_fmac_f32_e32 v99, v98, v98
	v_fmac_f32_e32 v101, v100, v100
	v_add_f32_e32 v98, v99, v101
	s_waitcnt vmcnt(19)
	v_pk_add_f32 v[94:95], v[90:91], v[200:201]
	v_pk_add_f32 v[92:93], v[88:89], v[198:199]
	v_cvt_pk_bf16_f32 v89, v94, v95
	v_cvt_pk_bf16_f32 v88, v92, v93
	global_store_dwordx2 v[102:103], v[88:89], off offset:32
	v_mul_f32_e32 v93, v93, v93
	v_mul_f32_e32 v95, v95, v95
	v_fmac_f32_e32 v93, v92, v92
	v_fmac_f32_e32 v95, v94, v94
	v_add_f32_e32 v92, v93, v95
	v_add_f32_e32 v92, v98, v92
	s_waitcnt vmcnt(19)
	v_pk_add_f32 v[90:91], v[86:87], v[204:205]
	v_pk_add_f32 v[88:89], v[84:85], v[202:203]
	v_cvt_pk_bf16_f32 v85, v90, v91
	v_cvt_pk_bf16_f32 v84, v88, v89
	global_store_dwordx2 v[102:103], v[84:85], off offset:256
	v_mul_f32_e32 v89, v89, v89
	v_mul_f32_e32 v91, v91, v91
	v_fmac_f32_e32 v89, v88, v88
	v_fmac_f32_e32 v91, v90, v90
	v_add_f32_e32 v88, v89, v91
	v_add_f32_e32 v88, v92, v88
	s_waitcnt vmcnt(19)
	v_pk_add_f32 v[82:83], v[82:83], v[208:209]
	v_pk_add_f32 v[84:85], v[80:81], v[206:207]
	v_mul_f32_e32 v81, v83, v83
	v_mul_f32_e32 v80, v85, v85
	v_fmac_f32_e32 v80, v84, v84
	v_fmac_f32_e32 v81, v82, v82
	v_add_f32_e32 v80, v80, v81
	v_add_f32_e32 v80, v88, v80
	ds_bpermute_b32 v81, v116, v80
	v_cvt_pk_bf16_f32 v84, v84, v85
	v_cvt_pk_bf16_f32 v85, v82, v83
	global_store_dwordx2 v[102:103], v[84:85], off offset:288
	s_waitcnt lgkmcnt(0)
	v_add_f32_e32 v80, v80, v81
	ds_bpermute_b32 v81, v114, v80
	s_and_saveexec_b64 s[40:41], s[2:3]
	s_cbranch_execz .LBB0_1460
	v_lshl_add_u64 v[82:83], v[96:97], 2, s[6:7]
	s_waitcnt lgkmcnt(0)
	v_add_f32_e32 v80, v80, v81
	global_atomic_add_f32 v[82:83], v80, off
.LBB0_1460:
	s_or_b64 exec, exec, s[40:41]
	v_add_u32_e32 v252, 0x90, v142
	v_ashrrev_i32_e32 v253, 31, v252
	v_lshlrev_b64 v[252:253], 10, v[252:253]
	v_lshl_add_u64 v[252:253], v[252:253], 0, v[140:141]
	v_lshl_add_u64 v[252:253], v[252:253], 2, s[12:13]
	global_load_dwordx4 v[162:165], v[252:253], off
	global_load_dwordx4 v[166:169], v[252:253], off offset:64
	global_load_dwordx4 v[170:173], v[252:253], off offset:512
	global_load_dwordx4 v[174:177], v[252:253], off offset:576
	v_add_u32_e32 v250, 0xa0, v142
	v_ashrrev_i32_e32 v251, 31, v250
	v_lshlrev_b64 v[250:251], 10, v[250:251]
	v_lshl_add_u64 v[250:251], v[250:251], 0, v[140:141]
	v_lshl_add_u64 v[250:251], v[250:251], 2, s[12:13]
	global_load_dwordx4 v[178:181], v[250:251], off
	global_load_dwordx4 v[182:185], v[250:251], off offset:64
	global_load_dwordx4 v[186:189], v[250:251], off offset:512
	global_load_dwordx4 v[190:193], v[250:251], off offset:576
	v_add_u32_e32 v252, 0xb0, v142
	v_ashrrev_i32_e32 v253, 31, v252
	v_lshlrev_b64 v[252:253], 10, v[252:253]
	v_lshl_add_u64 v[252:253], v[252:253], 0, v[140:141]
	v_lshl_add_u64 v[252:253], v[252:253], 2, s[12:13]
	global_load_dwordx4 v[194:197], v[252:253], off
	global_load_dwordx4 v[198:201], v[252:253], off offset:64
	global_load_dwordx4 v[202:205], v[252:253], off offset:512
	global_load_dwordx4 v[206:209], v[252:253], off offset:576
	v_or_b32_e32 v80, 48, v142
	s_waitcnt lgkmcnt(0)
	v_ashrrev_i32_e32 v81, 31, v80
	v_lshlrev_b64 v[82:83], 10, v[80:81]
	v_lshl_add_u64 v[86:87], v[82:83], 0, v[140:141]
	v_lshl_add_u64 v[88:89], v[86:87], 2, s[12:13]
	v_lshl_add_u64 v[86:87], v[86:87], 1, s[28:29]
	s_waitcnt vmcnt(31)
	v_pk_add_f32 v[84:85], v[78:79], v[212:213]
	v_pk_add_f32 v[82:83], v[76:77], v[210:211]
	v_cvt_pk_bf16_f32 v77, v84, v85
	v_cvt_pk_bf16_f32 v76, v82, v83
	global_store_dwordx2 v[86:87], v[76:77], off
	v_mul_f32_e32 v83, v83, v83
	v_mul_f32_e32 v85, v85, v85
	v_fmac_f32_e32 v83, v82, v82
	v_fmac_f32_e32 v85, v84, v84
	v_add_f32_e32 v82, v83, v85
	s_waitcnt vmcnt(31)
	v_pk_add_f32 v[78:79], v[74:75], v[224:225]
	v_pk_add_f32 v[76:77], v[72:73], v[222:223]
	v_cvt_pk_bf16_f32 v73, v78, v79
	v_cvt_pk_bf16_f32 v72, v76, v77
	global_store_dwordx2 v[86:87], v[72:73], off offset:32
	v_mul_f32_e32 v77, v77, v77
	v_mul_f32_e32 v79, v79, v79
	v_fmac_f32_e32 v77, v76, v76
	v_fmac_f32_e32 v79, v78, v78
	v_add_f32_e32 v76, v77, v79
	v_add_f32_e32 v76, v82, v76
	s_waitcnt vmcnt(31)
	v_pk_add_f32 v[74:75], v[70:71], v[228:229]
	v_pk_add_f32 v[72:73], v[68:69], v[226:227]
	v_cvt_pk_bf16_f32 v69, v74, v75
	v_cvt_pk_bf16_f32 v68, v72, v73
	global_store_dwordx2 v[86:87], v[68:69], off offset:256
	v_mul_f32_e32 v73, v73, v73
	v_mul_f32_e32 v75, v75, v75
	v_fmac_f32_e32 v73, v72, v72
	v_fmac_f32_e32 v75, v74, v74
	v_add_f32_e32 v72, v73, v75
	v_add_f32_e32 v72, v76, v72
	s_waitcnt vmcnt(31)
	v_pk_add_f32 v[66:67], v[66:67], v[232:233]
	v_pk_add_f32 v[68:69], v[64:65], v[230:231]
	v_mul_f32_e32 v65, v67, v67
	v_mul_f32_e32 v64, v69, v69
	v_fmac_f32_e32 v64, v68, v68
	v_fmac_f32_e32 v65, v66, v66
	v_add_f32_e32 v64, v64, v65
	v_add_f32_e32 v64, v72, v64
	ds_bpermute_b32 v65, v116, v64
	v_cvt_pk_bf16_f32 v68, v68, v69
	v_cvt_pk_bf16_f32 v69, v66, v67
	global_store_dwordx2 v[86:87], v[68:69], off offset:288
	s_waitcnt lgkmcnt(0)
	v_add_f32_e32 v64, v64, v65
	ds_bpermute_b32 v65, v114, v64
	s_and_saveexec_b64 s[40:41], s[2:3]
	s_cbranch_execz .LBB0_1462
	v_lshl_add_u64 v[66:67], v[80:81], 2, s[6:7]
	s_waitcnt lgkmcnt(0)
	v_add_f32_e32 v64, v64, v65
	global_atomic_add_f32 v[66:67], v64, off
.LBB0_1462:
	s_or_b64 exec, exec, s[40:41]
	v_add_u32_e32 v64, 0x80, v142
	s_waitcnt lgkmcnt(0)
	v_ashrrev_i32_e32 v65, 31, v64
	v_lshlrev_b64 v[66:67], 10, v[64:65]
	v_lshl_add_u64 v[70:71], v[66:67], 0, v[140:141]
	v_lshl_add_u64 v[72:73], v[70:71], 2, s[12:13]
	v_lshl_add_u64 v[70:71], v[70:71], 1, s[28:29]
	s_waitcnt vmcnt(31)
	v_pk_add_f32 v[68:69], v[62:63], v[236:237]
	v_pk_add_f32 v[66:67], v[60:61], v[234:235]
	v_cvt_pk_bf16_f32 v61, v68, v69
	v_cvt_pk_bf16_f32 v60, v66, v67
	global_store_dwordx2 v[70:71], v[60:61], off
	v_mul_f32_e32 v67, v67, v67
	v_mul_f32_e32 v69, v69, v69
	v_fmac_f32_e32 v67, v66, v66
	v_fmac_f32_e32 v69, v68, v68
	v_add_f32_e32 v66, v67, v69
	s_waitcnt vmcnt(31)
	v_pk_add_f32 v[62:63], v[58:59], v[240:241]
	v_pk_add_f32 v[60:61], v[56:57], v[238:239]
	v_cvt_pk_bf16_f32 v57, v62, v63
	v_cvt_pk_bf16_f32 v56, v60, v61
	global_store_dwordx2 v[70:71], v[56:57], off offset:32
	v_mul_f32_e32 v61, v61, v61
	v_mul_f32_e32 v63, v63, v63
	v_fmac_f32_e32 v61, v60, v60
	v_fmac_f32_e32 v63, v62, v62
	v_add_f32_e32 v60, v61, v63
	v_add_f32_e32 v60, v66, v60
	s_waitcnt vmcnt(31)
	v_pk_add_f32 v[58:59], v[54:55], v[244:245]
	v_pk_add_f32 v[56:57], v[52:53], v[242:243]
	v_cvt_pk_bf16_f32 v53, v58, v59
	v_cvt_pk_bf16_f32 v52, v56, v57
	global_store_dwordx2 v[70:71], v[52:53], off offset:256
	v_mul_f32_e32 v57, v57, v57
	v_mul_f32_e32 v59, v59, v59
	v_fmac_f32_e32 v57, v56, v56
	v_fmac_f32_e32 v59, v58, v58
	v_add_f32_e32 v56, v57, v59
	v_add_f32_e32 v56, v60, v56
	s_waitcnt vmcnt(31)
	v_pk_add_f32 v[50:51], v[50:51], v[248:249]
	v_pk_add_f32 v[52:53], v[48:49], v[246:247]
	v_mul_f32_e32 v49, v51, v51
	v_mul_f32_e32 v48, v53, v53
	v_fmac_f32_e32 v48, v52, v52
	v_fmac_f32_e32 v49, v50, v50
	v_add_f32_e32 v48, v48, v49
	v_add_f32_e32 v48, v56, v48
	ds_bpermute_b32 v49, v116, v48
	v_cvt_pk_bf16_f32 v52, v52, v53
	v_cvt_pk_bf16_f32 v53, v50, v51
	global_store_dwordx2 v[70:71], v[52:53], off offset:288
	s_waitcnt lgkmcnt(0)
	v_add_f32_e32 v48, v48, v49
	ds_bpermute_b32 v49, v114, v48
	s_and_saveexec_b64 s[40:41], s[2:3]
	s_cbranch_execz .LBB0_1464
	v_lshl_add_u64 v[50:51], v[64:65], 2, s[6:7]
	s_waitcnt lgkmcnt(0)
	v_add_f32_e32 v48, v48, v49
	global_atomic_add_f32 v[50:51], v48, off
.LBB0_1464:
	s_or_b64 exec, exec, s[40:41]
	v_add_u32_e32 v48, 0x90, v142
	s_waitcnt lgkmcnt(0)
	v_ashrrev_i32_e32 v49, 31, v48
	v_lshlrev_b64 v[50:51], 10, v[48:49]
	v_lshl_add_u64 v[54:55], v[50:51], 0, v[140:141]
	v_lshl_add_u64 v[56:57], v[54:55], 2, s[12:13]
	v_lshl_add_u64 v[54:55], v[54:55], 1, s[28:29]
	s_waitcnt vmcnt(19)
	v_pk_add_f32 v[52:53], v[46:47], v[164:165]
	v_pk_add_f32 v[50:51], v[44:45], v[162:163]
	v_cvt_pk_bf16_f32 v45, v52, v53
	v_cvt_pk_bf16_f32 v44, v50, v51
	global_store_dwordx2 v[54:55], v[44:45], off
	v_mul_f32_e32 v51, v51, v51
	v_mul_f32_e32 v53, v53, v53
	v_fmac_f32_e32 v51, v50, v50
	v_fmac_f32_e32 v53, v52, v52
	v_add_f32_e32 v50, v51, v53
	s_waitcnt vmcnt(19)
	v_pk_add_f32 v[46:47], v[42:43], v[168:169]
	v_pk_add_f32 v[44:45], v[40:41], v[166:167]
	v_cvt_pk_bf16_f32 v41, v46, v47
	v_cvt_pk_bf16_f32 v40, v44, v45
	global_store_dwordx2 v[54:55], v[40:41], off offset:32
	v_mul_f32_e32 v45, v45, v45
	v_mul_f32_e32 v47, v47, v47
	v_fmac_f32_e32 v45, v44, v44
	v_fmac_f32_e32 v47, v46, v46
	v_add_f32_e32 v44, v45, v47
	v_add_f32_e32 v44, v50, v44
	s_waitcnt vmcnt(19)
	v_pk_add_f32 v[42:43], v[38:39], v[172:173]
	v_pk_add_f32 v[40:41], v[36:37], v[170:171]
	v_cvt_pk_bf16_f32 v37, v42, v43
	v_cvt_pk_bf16_f32 v36, v40, v41
	global_store_dwordx2 v[54:55], v[36:37], off offset:256
	v_mul_f32_e32 v41, v41, v41
	v_mul_f32_e32 v43, v43, v43
	v_fmac_f32_e32 v41, v40, v40
	v_fmac_f32_e32 v43, v42, v42
	v_add_f32_e32 v40, v41, v43
	v_add_f32_e32 v40, v44, v40
	s_waitcnt vmcnt(19)
	v_pk_add_f32 v[34:35], v[34:35], v[176:177]
	v_pk_add_f32 v[36:37], v[32:33], v[174:175]
	v_mul_f32_e32 v33, v35, v35
	v_mul_f32_e32 v32, v37, v37
	v_fmac_f32_e32 v32, v36, v36
	v_fmac_f32_e32 v33, v34, v34
	v_add_f32_e32 v32, v32, v33
	v_add_f32_e32 v32, v40, v32
	ds_bpermute_b32 v33, v116, v32
	v_cvt_pk_bf16_f32 v36, v36, v37
	v_cvt_pk_bf16_f32 v37, v34, v35
	global_store_dwordx2 v[54:55], v[36:37], off offset:288
	s_waitcnt lgkmcnt(0)
	v_add_f32_e32 v32, v32, v33
	ds_bpermute_b32 v33, v114, v32
	s_and_saveexec_b64 s[40:41], s[2:3]
	s_cbranch_execz .LBB0_1466
	v_lshl_add_u64 v[34:35], v[48:49], 2, s[6:7]
	s_waitcnt lgkmcnt(0)
	v_add_f32_e32 v32, v32, v33
	global_atomic_add_f32 v[34:35], v32, off
.LBB0_1466:
	s_or_b64 exec, exec, s[40:41]
	v_add_u32_e32 v32, 0xa0, v142
	s_waitcnt lgkmcnt(0)
	v_ashrrev_i32_e32 v33, 31, v32
	v_lshlrev_b64 v[34:35], 10, v[32:33]
	v_lshl_add_u64 v[38:39], v[34:35], 0, v[140:141]
	v_lshl_add_u64 v[40:41], v[38:39], 2, s[12:13]
	v_lshl_add_u64 v[38:39], v[38:39], 1, s[28:29]
	s_waitcnt vmcnt(19)
	v_pk_add_f32 v[36:37], v[30:31], v[180:181]
	v_pk_add_f32 v[34:35], v[28:29], v[178:179]
	v_cvt_pk_bf16_f32 v29, v36, v37
	v_cvt_pk_bf16_f32 v28, v34, v35
	global_store_dwordx2 v[38:39], v[28:29], off
	v_mul_f32_e32 v35, v35, v35
	v_mul_f32_e32 v37, v37, v37
	v_fmac_f32_e32 v35, v34, v34
	v_fmac_f32_e32 v37, v36, v36
	v_add_f32_e32 v34, v35, v37
	s_waitcnt vmcnt(19)
	v_pk_add_f32 v[30:31], v[26:27], v[184:185]
	v_pk_add_f32 v[28:29], v[24:25], v[182:183]
	v_cvt_pk_bf16_f32 v25, v30, v31
	v_cvt_pk_bf16_f32 v24, v28, v29
	global_store_dwordx2 v[38:39], v[24:25], off offset:32
	v_mul_f32_e32 v29, v29, v29
	v_mul_f32_e32 v31, v31, v31
	v_fmac_f32_e32 v29, v28, v28
	v_fmac_f32_e32 v31, v30, v30
	v_add_f32_e32 v28, v29, v31
	v_add_f32_e32 v28, v34, v28
	s_waitcnt vmcnt(19)
	v_pk_add_f32 v[26:27], v[22:23], v[188:189]
	v_pk_add_f32 v[24:25], v[20:21], v[186:187]
	v_cvt_pk_bf16_f32 v21, v26, v27
	v_cvt_pk_bf16_f32 v20, v24, v25
	global_store_dwordx2 v[38:39], v[20:21], off offset:256
	v_mul_f32_e32 v25, v25, v25
	v_mul_f32_e32 v27, v27, v27
	v_fmac_f32_e32 v25, v24, v24
	v_fmac_f32_e32 v27, v26, v26
	v_add_f32_e32 v24, v25, v27
	v_add_f32_e32 v24, v28, v24
	s_waitcnt vmcnt(19)
	v_pk_add_f32 v[18:19], v[18:19], v[192:193]
	v_pk_add_f32 v[20:21], v[16:17], v[190:191]
	v_mul_f32_e32 v17, v19, v19
	v_mul_f32_e32 v16, v21, v21
	v_fmac_f32_e32 v16, v20, v20
	v_fmac_f32_e32 v17, v18, v18
	v_add_f32_e32 v16, v16, v17
	v_add_f32_e32 v16, v24, v16
	ds_bpermute_b32 v17, v116, v16
	v_cvt_pk_bf16_f32 v20, v20, v21
	v_cvt_pk_bf16_f32 v21, v18, v19
	global_store_dwordx2 v[38:39], v[20:21], off offset:288
	s_waitcnt lgkmcnt(0)
	v_add_f32_e32 v16, v16, v17
	ds_bpermute_b32 v17, v114, v16
	s_and_saveexec_b64 s[40:41], s[2:3]
	s_cbranch_execz .LBB0_1468
	v_lshl_add_u64 v[18:19], v[32:33], 2, s[6:7]
	s_waitcnt lgkmcnt(0)
	v_add_f32_e32 v16, v16, v17
	global_atomic_add_f32 v[18:19], v16, off
.LBB0_1468:
	s_or_b64 exec, exec, s[40:41]
	v_add_u32_e32 v16, 0xb0, v142
	s_waitcnt lgkmcnt(0)
	v_ashrrev_i32_e32 v17, 31, v16
	v_lshlrev_b64 v[18:19], 10, v[16:17]
	v_lshl_add_u64 v[22:23], v[18:19], 0, v[140:141]
	v_lshl_add_u64 v[24:25], v[22:23], 2, s[12:13]
	v_lshl_add_u64 v[22:23], v[22:23], 1, s[28:29]
	s_waitcnt vmcnt(19)
	v_pk_add_f32 v[20:21], v[14:15], v[196:197]
	v_pk_add_f32 v[18:19], v[12:13], v[194:195]
	v_cvt_pk_bf16_f32 v13, v20, v21
	v_cvt_pk_bf16_f32 v12, v18, v19
	global_store_dwordx2 v[22:23], v[12:13], off
	v_mul_f32_e32 v19, v19, v19
	v_mul_f32_e32 v21, v21, v21
	v_fmac_f32_e32 v19, v18, v18
	v_fmac_f32_e32 v21, v20, v20
	v_add_f32_e32 v18, v19, v21
	s_waitcnt vmcnt(19)
	v_pk_add_f32 v[14:15], v[10:11], v[200:201]
	v_pk_add_f32 v[12:13], v[8:9], v[198:199]
	v_cvt_pk_bf16_f32 v9, v14, v15
	v_cvt_pk_bf16_f32 v8, v12, v13
	global_store_dwordx2 v[22:23], v[8:9], off offset:32
	v_mul_f32_e32 v13, v13, v13
	v_mul_f32_e32 v15, v15, v15
	v_fmac_f32_e32 v13, v12, v12
	v_fmac_f32_e32 v15, v14, v14
	v_add_f32_e32 v12, v13, v15
	v_add_f32_e32 v12, v18, v12
	s_waitcnt vmcnt(19)
	v_pk_add_f32 v[10:11], v[6:7], v[204:205]
	v_pk_add_f32 v[8:9], v[4:5], v[202:203]
	v_cvt_pk_bf16_f32 v5, v10, v11
	v_cvt_pk_bf16_f32 v4, v8, v9
	global_store_dwordx2 v[22:23], v[4:5], off offset:256
	v_mul_f32_e32 v9, v9, v9
	v_mul_f32_e32 v11, v11, v11
	v_fmac_f32_e32 v9, v8, v8
	v_fmac_f32_e32 v11, v10, v10
	v_add_f32_e32 v8, v9, v11
	v_add_f32_e32 v8, v12, v8
	s_waitcnt vmcnt(19)
	v_pk_add_f32 v[2:3], v[2:3], v[208:209]
	v_pk_add_f32 v[4:5], v[0:1], v[206:207]
	v_mul_f32_e32 v1, v3, v3
	v_mul_f32_e32 v0, v5, v5
	v_fmac_f32_e32 v0, v4, v4
	v_fmac_f32_e32 v1, v2, v2
	v_add_f32_e32 v0, v0, v1
	v_add_f32_e32 v0, v8, v0
	ds_bpermute_b32 v1, v116, v0
	v_cvt_pk_bf16_f32 v4, v4, v5
	v_cvt_pk_bf16_f32 v5, v2, v3
	global_store_dwordx2 v[22:23], v[4:5], off offset:288
	s_waitcnt lgkmcnt(0)
	v_add_f32_e32 v0, v0, v1
	ds_bpermute_b32 v1, v114, v0
	s_and_saveexec_b64 s[40:41], s[2:3]
	s_cbranch_execz .LBB0_1470
	v_lshl_add_u64 v[2:3], v[16:17], 2, s[6:7]
	s_waitcnt lgkmcnt(0)
	v_add_f32_e32 v0, v0, v1
	global_atomic_add_f32 v[2:3], v0, off

.LBB0_1908:
	v_lshl_add_u32 v144, s55, 8, v146
	v_lshl_add_u32 v142, s56, 8, v148
	v_ashrrev_i32_e32 v145, 31, v144
	v_ashrrev_i32_e32 v143, 31, v142
	v_lshlrev_b64 v[140:141], 10, v[144:145]
	v_lshl_add_u64 v[140:141], v[140:141], 0, v[142:143]
	v_lshl_add_u64 v[152:153], v[140:141], 1, s[26:27]
	global_load_dwordx2 v[160:161], v[152:153], off
	global_load_dwordx2 v[162:163], v[152:153], off offset:32
	global_load_dwordx2 v[164:165], v[152:153], off offset:256
	global_load_dwordx2 v[166:167], v[152:153], off offset:288
	v_or_b32_e32 v230, 16, v144
	v_ashrrev_i32_e32 v231, 31, v230
	v_lshlrev_b64 v[230:231], 10, v[230:231]
	v_lshl_add_u64 v[230:231], v[230:231], 0, v[142:143]
	v_lshl_add_u64 v[230:231], v[230:231], 1, s[26:27]
	global_load_dwordx2 v[168:169], v[230:231], off
	global_load_dwordx2 v[170:171], v[230:231], off offset:32
	global_load_dwordx2 v[172:173], v[230:231], off offset:256
	global_load_dwordx2 v[174:175], v[230:231], off offset:288
	v_or_b32_e32 v232, 32, v144
	v_ashrrev_i32_e32 v233, 31, v232
	v_lshlrev_b64 v[232:233], 10, v[232:233]
	v_lshl_add_u64 v[232:233], v[232:233], 0, v[142:143]
	v_lshl_add_u64 v[232:233], v[232:233], 1, s[26:27]
	global_load_dwordx2 v[176:177], v[232:233], off
	global_load_dwordx2 v[178:179], v[232:233], off offset:32
	global_load_dwordx2 v[180:181], v[232:233], off offset:256
	global_load_dwordx2 v[182:183], v[232:233], off offset:288
	v_or_b32_e32 v230, 48, v144
	v_ashrrev_i32_e32 v231, 31, v230
	v_lshlrev_b64 v[230:231], 10, v[230:231]
	v_lshl_add_u64 v[230:231], v[230:231], 0, v[142:143]
	v_lshl_add_u64 v[230:231], v[230:231], 1, s[26:27]
	global_load_dwordx2 v[184:185], v[230:231], off
	global_load_dwordx2 v[186:187], v[230:231], off offset:32
	global_load_dwordx2 v[188:189], v[230:231], off offset:256
	global_load_dwordx2 v[190:191], v[230:231], off offset:288
	v_lshl_add_u64 v[232:233], v[140:141], 0, s[14:15]
	v_lshl_add_u64 v[232:233], v[232:233], 1, s[26:27]
	global_load_dwordx2 v[192:193], v[232:233], off
	global_load_dwordx2 v[194:195], v[232:233], off offset:32
	global_load_dwordx2 v[196:197], v[232:233], off offset:256
	global_load_dwordx2 v[198:199], v[232:233], off offset:288
	v_lshl_add_u64 v[230:231], v[140:141], 0, s[16:17]
	v_lshl_add_u64 v[230:231], v[230:231], 1, s[26:27]
	global_load_dwordx2 v[200:201], v[230:231], off
	global_load_dwordx2 v[202:203], v[230:231], off offset:32
	global_load_dwordx2 v[204:205], v[230:231], off offset:256
	global_load_dwordx2 v[206:207], v[230:231], off offset:288
	v_lshl_add_u64 v[232:233], v[140:141], 0, s[18:19]
	v_lshl_add_u64 v[232:233], v[232:233], 1, s[26:27]
	global_load_dwordx2 v[208:209], v[232:233], off
	global_load_dwordx2 v[210:211], v[232:233], off offset:32
	global_load_dwordx2 v[212:213], v[232:233], off offset:256
	global_load_dwordx2 v[214:215], v[232:233], off offset:288
	v_lshl_add_u64 v[230:231], v[140:141], 0, s[20:21]
	v_lshl_add_u64 v[230:231], v[230:231], 1, s[26:27]
	global_load_dwordx2 v[222:223], v[230:231], off
	global_load_dwordx2 v[224:225], v[230:231], off offset:32
	global_load_dwordx2 v[226:227], v[230:231], off offset:256
	global_load_dwordx2 v[228:229], v[230:231], off offset:288
	s_nop 0
	v_lshl_add_u64 v[156:157], v[140:141], 2, s[4:5]
	s_and_b64 vcc, exec, s[0:1]
	s_mov_b64 s[0:1], -1
	s_waitcnt vmcnt(31)
	v_lshlrev_b32_e32 v158, 16, v160
	v_and_b32_e32 v159, 0xffff0000, v160
	v_lshlrev_b32_e32 v154, 16, v161
	v_and_b32_e32 v155, 0xffff0000, v161
	v_pk_add_f32 v[126:127], v[126:127], v[154:155]
	v_pk_add_f32 v[124:125], v[124:125], v[158:159]
	global_store_dwordx4 v[156:157], v[124:127], off
	s_nop 0
	s_waitcnt vmcnt(31)
	v_lshlrev_b32_e32 v126, 16, v162
	v_and_b32_e32 v127, 0xffff0000, v162
	v_lshlrev_b32_e32 v124, 16, v163
	v_and_b32_e32 v125, 0xffff0000, v163
	v_pk_add_f32 v[122:123], v[122:123], v[124:125]
	v_pk_add_f32 v[120:121], v[120:121], v[126:127]
	global_store_dwordx4 v[156:157], v[120:123], off offset:64
	s_nop 0
	s_waitcnt vmcnt(31)
	v_lshlrev_b32_e32 v122, 16, v164
	v_and_b32_e32 v123, 0xffff0000, v164
	v_lshlrev_b32_e32 v120, 16, v165
	v_and_b32_e32 v121, 0xffff0000, v165
	v_pk_add_f32 v[118:119], v[118:119], v[120:121]
	v_pk_add_f32 v[116:117], v[116:117], v[122:123]
	global_store_dwordx4 v[156:157], v[116:119], off offset:512
	s_nop 0
	s_waitcnt vmcnt(31)
	v_lshlrev_b32_e32 v122, 16, v166
	v_or_b32_e32 v118, 16, v144
	v_ashrrev_i32_e32 v119, 31, v118
	v_lshlrev_b64 v[118:119], 10, v[118:119]
	v_and_b32_e32 v123, 0xffff0000, v166
	v_lshlrev_b32_e32 v116, 16, v167
	v_and_b32_e32 v117, 0xffff0000, v167
	v_lshl_add_u64 v[118:119], v[118:119], 0, v[142:143]
	v_pk_add_f32 v[110:111], v[110:111], v[116:117]
	v_pk_add_f32 v[108:109], v[108:109], v[122:123]
	v_lshl_add_u64 v[120:121], v[118:119], 1, s[26:27]
	global_store_dwordx4 v[156:157], v[108:111], off offset:576
	s_nop 0
	v_lshl_add_u64 v[116:117], v[118:119], 2, s[4:5]
	s_waitcnt vmcnt(31)
	v_lshlrev_b32_e32 v118, 16, v168
	v_and_b32_e32 v119, 0xffff0000, v168
	v_lshlrev_b32_e32 v108, 16, v169
	v_and_b32_e32 v109, 0xffff0000, v169
	v_pk_add_f32 v[110:111], v[114:115], v[108:109]
	v_pk_add_f32 v[108:109], v[112:113], v[118:119]
	global_store_dwordx4 v[116:117], v[108:111], off
	s_nop 0
	s_waitcnt vmcnt(31)
	v_lshlrev_b32_e32 v110, 16, v170
	v_and_b32_e32 v111, 0xffff0000, v170
	v_lshlrev_b32_e32 v108, 16, v171
	v_and_b32_e32 v109, 0xffff0000, v171
	v_pk_add_f32 v[106:107], v[106:107], v[108:109]
	v_pk_add_f32 v[104:105], v[104:105], v[110:111]
	global_store_dwordx4 v[116:117], v[104:107], off offset:64
	s_nop 0
	s_waitcnt vmcnt(31)
	v_lshlrev_b32_e32 v106, 16, v172
	v_and_b32_e32 v107, 0xffff0000, v172
	v_lshlrev_b32_e32 v104, 16, v173
	v_and_b32_e32 v105, 0xffff0000, v173
	v_pk_add_f32 v[102:103], v[102:103], v[104:105]
	v_pk_add_f32 v[100:101], v[100:101], v[106:107]
	global_store_dwordx4 v[116:117], v[100:103], off offset:512
	s_nop 0
	s_waitcnt vmcnt(31)
	v_lshlrev_b32_e32 v106, 16, v174
	v_or_b32_e32 v102, 32, v144
	v_ashrrev_i32_e32 v103, 31, v102
	v_lshlrev_b64 v[102:103], 10, v[102:103]
	v_and_b32_e32 v107, 0xffff0000, v174
	v_lshlrev_b32_e32 v100, 16, v175
	v_and_b32_e32 v101, 0xffff0000, v175
	v_lshl_add_u64 v[102:103], v[102:103], 0, v[142:143]
	v_pk_add_f32 v[94:95], v[94:95], v[100:101]
	v_pk_add_f32 v[92:93], v[92:93], v[106:107]
	v_lshl_add_u64 v[104:105], v[102:103], 1, s[26:27]
	global_store_dwordx4 v[116:117], v[92:95], off offset:576
	s_nop 0
	v_lshl_add_u64 v[100:101], v[102:103], 2, s[4:5]
	s_waitcnt vmcnt(31)
	v_lshlrev_b32_e32 v102, 16, v176
	v_and_b32_e32 v103, 0xffff0000, v176
	v_lshlrev_b32_e32 v92, 16, v177
	v_and_b32_e32 v93, 0xffff0000, v177
	v_pk_add_f32 v[94:95], v[98:99], v[92:93]
	v_pk_add_f32 v[92:93], v[96:97], v[102:103]
	global_store_dwordx4 v[100:101], v[92:95], off
	s_nop 0
	s_waitcnt vmcnt(31)
	v_lshlrev_b32_e32 v94, 16, v178
	v_and_b32_e32 v95, 0xffff0000, v178
	v_lshlrev_b32_e32 v92, 16, v179
	v_and_b32_e32 v93, 0xffff0000, v179
	v_pk_add_f32 v[90:91], v[90:91], v[92:93]
	v_pk_add_f32 v[88:89], v[88:89], v[94:95]
	global_store_dwordx4 v[100:101], v[88:91], off offset:64
	s_nop 0
	s_waitcnt vmcnt(31)
	v_lshlrev_b32_e32 v90, 16, v180
	v_and_b32_e32 v91, 0xffff0000, v180
	v_lshlrev_b32_e32 v88, 16, v181
	v_and_b32_e32 v89, 0xffff0000, v181
	v_pk_add_f32 v[86:87], v[86:87], v[88:89]
	v_pk_add_f32 v[84:85], v[84:85], v[90:91]
	global_store_dwordx4 v[100:101], v[84:87], off offset:512
	s_nop 0
	s_waitcnt vmcnt(31)
	v_lshlrev_b32_e32 v90, 16, v182
	v_or_b32_e32 v86, 48, v144
	v_ashrrev_i32_e32 v87, 31, v86
	v_lshlrev_b64 v[86:87], 10, v[86:87]
	v_and_b32_e32 v91, 0xffff0000, v182
	v_lshlrev_b32_e32 v84, 16, v183
	v_and_b32_e32 v85, 0xffff0000, v183
	v_lshl_add_u64 v[86:87], v[86:87], 0, v[142:143]
	v_pk_add_f32 v[78:79], v[78:79], v[84:85]
	v_pk_add_f32 v[76:77], v[76:77], v[90:91]
	v_lshl_add_u64 v[88:89], v[86:87], 1, s[26:27]
	global_store_dwordx4 v[100:101], v[76:79], off offset:576
	s_nop 0
	v_lshl_add_u64 v[84:85], v[86:87], 2, s[4:5]
	s_waitcnt vmcnt(31)
	v_lshlrev_b32_e32 v86, 16, v184
	v_and_b32_e32 v87, 0xffff0000, v184
	v_lshlrev_b32_e32 v76, 16, v185
	v_and_b32_e32 v77, 0xffff0000, v185
	v_pk_add_f32 v[78:79], v[82:83], v[76:77]
	v_pk_add_f32 v[76:77], v[80:81], v[86:87]
	global_store_dwordx4 v[84:85], v[76:79], off
	s_nop 0
	s_waitcnt vmcnt(31)
	v_lshlrev_b32_e32 v78, 16, v186
	v_and_b32_e32 v79, 0xffff0000, v186
	v_lshlrev_b32_e32 v76, 16, v187
	v_and_b32_e32 v77, 0xffff0000, v187
	v_pk_add_f32 v[74:75], v[74:75], v[76:77]
	v_pk_add_f32 v[72:73], v[72:73], v[78:79]
	global_store_dwordx4 v[84:85], v[72:75], off offset:64
	s_nop 0
	s_waitcnt vmcnt(31)
	v_lshlrev_b32_e32 v74, 16, v188
	v_and_b32_e32 v75, 0xffff0000, v188
	v_lshlrev_b32_e32 v72, 16, v189
	v_and_b32_e32 v73, 0xffff0000, v189
	v_pk_add_f32 v[70:71], v[70:71], v[72:73]
	v_pk_add_f32 v[68:69], v[68:69], v[74:75]
	global_store_dwordx4 v[84:85], v[68:71], off offset:512
	s_nop 0
	s_waitcnt vmcnt(31)
	v_lshlrev_b32_e32 v74, 16, v190
	v_and_b32_e32 v75, 0xffff0000, v190
	v_lshlrev_b32_e32 v68, 16, v191
	v_and_b32_e32 v69, 0xffff0000, v191
	v_lshl_add_u64 v[70:71], v[140:141], 0, s[14:15]
	v_pk_add_f32 v[66:67], v[66:67], v[68:69]
	v_pk_add_f32 v[64:65], v[64:65], v[74:75]
	v_lshl_add_u64 v[72:73], v[70:71], 1, s[26:27]
	global_store_dwordx4 v[84:85], v[64:67], off offset:576
	s_nop 0
	s_waitcnt vmcnt(31)
	v_lshlrev_b32_e32 v68, 16, v192
	v_and_b32_e32 v69, 0xffff0000, v192
	v_lshlrev_b32_e32 v64, 16, v193
	v_and_b32_e32 v65, 0xffff0000, v193
	v_lshl_add_u64 v[66:67], v[70:71], 2, s[4:5]
	v_pk_add_f32 v[62:63], v[62:63], v[64:65]
	v_pk_add_f32 v[60:61], v[60:61], v[68:69]
	global_store_dwordx4 v[66:67], v[60:63], off
	s_nop 0
	s_waitcnt vmcnt(31)
	v_lshlrev_b32_e32 v62, 16, v194
	v_and_b32_e32 v63, 0xffff0000, v194
	v_lshlrev_b32_e32 v60, 16, v195
	v_and_b32_e32 v61, 0xffff0000, v195
	v_pk_add_f32 v[58:59], v[58:59], v[60:61]
	v_pk_add_f32 v[56:57], v[56:57], v[62:63]
	global_store_dwordx4 v[66:67], v[56:59], off offset:64
	s_nop 0
	s_waitcnt vmcnt(31)
	v_lshlrev_b32_e32 v58, 16, v196
	v_and_b32_e32 v59, 0xffff0000, v196
	v_lshlrev_b32_e32 v56, 16, v197
	v_and_b32_e32 v57, 0xffff0000, v197
	v_pk_add_f32 v[54:55], v[54:55], v[56:57]
	v_pk_add_f32 v[52:53], v[52:53], v[58:59]
	global_store_dwordx4 v[66:67], v[52:55], off offset:512
	s_nop 0
	s_waitcnt vmcnt(31)
	v_lshlrev_b32_e32 v58, 16, v198
	v_and_b32_e32 v59, 0xffff0000, v198
	v_lshlrev_b32_e32 v52, 16, v199
	v_and_b32_e32 v53, 0xffff0000, v199
	v_lshl_add_u64 v[54:55], v[140:141], 0, s[16:17]
	v_pk_add_f32 v[46:47], v[46:47], v[52:53]
	v_pk_add_f32 v[44:45], v[44:45], v[58:59]
	v_lshl_add_u64 v[56:57], v[54:55], 1, s[26:27]
	global_store_dwordx4 v[66:67], v[44:47], off offset:576
	s_nop 0
	v_lshl_add_u64 v[52:53], v[54:55], 2, s[4:5]
	s_waitcnt vmcnt(31)
	v_lshlrev_b32_e32 v54, 16, v200
	v_and_b32_e32 v55, 0xffff0000, v200
	v_lshlrev_b32_e32 v44, 16, v201
	v_and_b32_e32 v45, 0xffff0000, v201
	v_pk_add_f32 v[46:47], v[50:51], v[44:45]
	v_pk_add_f32 v[44:45], v[48:49], v[54:55]
	global_store_dwordx4 v[52:53], v[44:47], off
	s_nop 0
	s_waitcnt vmcnt(31)
	v_lshlrev_b32_e32 v46, 16, v202
	v_and_b32_e32 v47, 0xffff0000, v202
	v_lshlrev_b32_e32 v44, 16, v203
	v_and_b32_e32 v45, 0xffff0000, v203
	v_pk_add_f32 v[42:43], v[42:43], v[44:45]
	v_pk_add_f32 v[40:41], v[40:41], v[46:47]
	global_store_dwordx4 v[52:53], v[40:43], off offset:64
	s_nop 0
	s_waitcnt vmcnt(31)
	v_lshlrev_b32_e32 v42, 16, v204
	v_and_b32_e32 v43, 0xffff0000, v204
	v_lshlrev_b32_e32 v40, 16, v205
	v_and_b32_e32 v41, 0xffff0000, v205
	v_pk_add_f32 v[38:39], v[38:39], v[40:41]
	v_pk_add_f32 v[36:37], v[36:37], v[42:43]
	global_store_dwordx4 v[52:53], v[36:39], off offset:512
	s_nop 0
	s_waitcnt vmcnt(31)
	v_lshlrev_b32_e32 v42, 16, v206
	v_and_b32_e32 v43, 0xffff0000, v206
	v_lshlrev_b32_e32 v36, 16, v207
	v_and_b32_e32 v37, 0xffff0000, v207
	v_lshl_add_u64 v[38:39], v[140:141], 0, s[18:19]
	v_pk_add_f32 v[30:31], v[30:31], v[36:37]
	v_pk_add_f32 v[28:29], v[28:29], v[42:43]
	v_lshl_add_u64 v[40:41], v[38:39], 1, s[26:27]
	global_store_dwordx4 v[52:53], v[28:31], off offset:576
	s_nop 0
	v_lshl_add_u64 v[36:37], v[38:39], 2, s[4:5]
	s_waitcnt vmcnt(31)
	v_lshlrev_b32_e32 v38, 16, v208
	v_and_b32_e32 v39, 0xffff0000, v208
	v_lshlrev_b32_e32 v28, 16, v209
	v_and_b32_e32 v29, 0xffff0000, v209
	v_pk_add_f32 v[30:31], v[34:35], v[28:29]
	v_pk_add_f32 v[28:29], v[32:33], v[38:39]
	global_store_dwordx4 v[36:37], v[28:31], off
	s_nop 0
	s_waitcnt vmcnt(31)
	v_lshlrev_b32_e32 v30, 16, v210
	v_and_b32_e32 v31, 0xffff0000, v210
	v_lshlrev_b32_e32 v28, 16, v211
	v_and_b32_e32 v29, 0xffff0000, v211
	v_pk_add_f32 v[26:27], v[26:27], v[28:29]
	v_pk_add_f32 v[24:25], v[24:25], v[30:31]
	global_store_dwordx4 v[36:37], v[24:27], off offset:64
	s_nop 0
	s_waitcnt vmcnt(31)
	v_lshlrev_b32_e32 v26, 16, v212
	v_and_b32_e32 v27, 0xffff0000, v212
	v_lshlrev_b32_e32 v24, 16, v213
	v_and_b32_e32 v25, 0xffff0000, v213
	v_pk_add_f32 v[22:23], v[22:23], v[24:25]
	v_pk_add_f32 v[20:21], v[20:21], v[26:27]
	global_store_dwordx4 v[36:37], v[20:23], off offset:512
	s_nop 0
	s_waitcnt vmcnt(31)
	v_lshlrev_b32_e32 v26, 16, v214
	v_and_b32_e32 v27, 0xffff0000, v214
	v_lshlrev_b32_e32 v20, 16, v215
	v_and_b32_e32 v21, 0xffff0000, v215
	v_lshl_add_u64 v[22:23], v[140:141], 0, s[20:21]
	v_pk_add_f32 v[14:15], v[14:15], v[20:21]
	v_pk_add_f32 v[12:13], v[12:13], v[26:27]
	v_lshl_add_u64 v[24:25], v[22:23], 1, s[26:27]
	global_store_dwordx4 v[36:37], v[12:15], off offset:576
	s_nop 0
	v_lshl_add_u64 v[20:21], v[22:23], 2, s[4:5]
	s_waitcnt vmcnt(31)
	v_lshlrev_b32_e32 v22, 16, v222
	v_and_b32_e32 v23, 0xffff0000, v222
	v_lshlrev_b32_e32 v12, 16, v223
	v_and_b32_e32 v13, 0xffff0000, v223
	v_pk_add_f32 v[14:15], v[18:19], v[12:13]
	v_pk_add_f32 v[12:13], v[16:17], v[22:23]
	global_store_dwordx4 v[20:21], v[12:15], off
	s_nop 0
	s_waitcnt vmcnt(31)
	v_lshlrev_b32_e32 v14, 16, v224
	v_and_b32_e32 v15, 0xffff0000, v224
	v_lshlrev_b32_e32 v12, 16, v225
	v_and_b32_e32 v13, 0xffff0000, v225
	v_pk_add_f32 v[10:11], v[10:11], v[12:13]
	v_pk_add_f32 v[8:9], v[8:9], v[14:15]
	global_store_dwordx4 v[20:21], v[8:11], off offset:64
	s_nop 0
	s_waitcnt vmcnt(31)
	v_lshlrev_b32_e32 v10, 16, v226
	v_and_b32_e32 v11, 0xffff0000, v226
	v_lshlrev_b32_e32 v8, 16, v227
	v_and_b32_e32 v9, 0xffff0000, v227
	v_pk_add_f32 v[6:7], v[6:7], v[8:9]
	v_pk_add_f32 v[4:5], v[4:5], v[10:11]
	global_store_dwordx4 v[20:21], v[4:7], off offset:512
	s_nop 0
	s_waitcnt vmcnt(31)
	v_lshlrev_b32_e32 v6, 16, v228
	v_and_b32_e32 v7, 0xffff0000, v228
	v_lshlrev_b32_e32 v4, 16, v229
	v_and_b32_e32 v5, 0xffff0000, v229
	v_pk_add_f32 v[2:3], v[2:3], v[4:5]
	v_pk_add_f32 v[0:1], v[0:1], v[6:7]
	global_store_dwordx4 v[20:21], v[0:3], off offset:576
	s_cbranch_vccnz .LBB0_1893
	s_andn2_b64 vcc, exec, s[6:7]
	s_cbranch_vccnz .LBB0_1892
	s_barrier
	s_branch .LBB0_1892
